# P10 (FFN down GEMM, K=5632): workgroup->tile order 4 row-tiles x 8 column-tiles per XCD round so each A panel is fetched once
# speedup vs baseline: 1.0540x; 1.0005x over previous
;     __host__ __device__ bool next(int i, Unit& u) const {
;         const long L = (long)i * G + c; if (L >= nwg) return false;
;         int wgid = (int)L; { const int q = nwg / NXCD, r = nwg % NXCD, xcd = wgid % NXCD, off = wgid / NXCD; wgid = (xcd < r ? xcd * (q + 1) : r * (q + 1) + (xcd - r) * q) + off; }
;         const int nig = WGM * nN, gid = wgid / nig, fm = gid * WGM, gsz = (nM - fm) < WGM ? (nM - fm) : WGM;
;         u.pm = fm + ((wgid % nig) % gsz); u.pn = (wgid % nig) / gsz; return true;
;     }
.LBB0_976:
	s_add_i32 s2, s7, s4
	s_lshr_b32 s5, s2, 5
	s_and_b32 s4, s2, 31
	s_and_b32 s7, s4, 3
	s_lshl_b32 s5, s5, 2
	s_add_i32 s20, s5, s7
	s_lshr_b32 s59, s4, 2

;     __host__ __device__ bool next(int i, Unit& u) const {
;         const long L = (long)i * G + c; if (L >= nwg) return false;
;         int wgid = (int)L; { const int q = nwg / NXCD, r = nwg % NXCD, xcd = wgid % NXCD, off = wgid / NXCD; wgid = (xcd < r ? xcd * (q + 1) : r * (q + 1) + (xcd - r) * q) + off; }
;         const int nig = WGM * nN, gid = wgid / nig, fm = gid * WGM, gsz = (nM - fm) < WGM ? (nM - fm) : WGM;
;         u.pm = fm + ((wgid % nig) % gsz); u.pn = (wgid % nig) / gsz; return true;
;     }
; template <class Epi, class Sched, bool ALIGN_EPI = false, bool SP2 = false>
; __device__ __forceinline__ void gemm_phase(PG8_LAS unsigned char* lds, const Gemm g, const Sched& S, const Epi& E) {
;     ...
;         const bool has_next = S.next(ui + 1, nxt);
;         const char* nA = has_next ? (const char*)g.A + (size_t)nxt.pm * tstep : cA; const char* nB = has_next ? (const char*)g.Bt + (size_t)nxt.pn * tstep : cB;
.LBB0_988:
	s_ashr_i32 s6, s28, 3
	s_add_i32 s6, s40, s6
	s_lshr_b32 s28, s6, 5
	s_lshl_b32 s28, s28, 2
	s_and_b32 s7, s6, 31
	s_and_b32 s6, s7, 3
	s_lshr_b32 s57, s7, 2
	s_add_i32 s58, s28, s6
